# HGRN2/GLA pre-pass rewritten by hand: per-token decay terms cached in registers across the two passes, scalar address math, low-rank gate row fetched with scalar loads, no recompute
# speedup vs baseline: 1.0131x; 1.0092x over previous
.Lpre_init:
	v_and_b32_e32 v140, 0x7f, v156
	v_lshlrev_b32_e32 v141, 1, v140
	v_lshlrev_b32_e32 v140, 2, v140
	v_and_b32_e32 v142, 63, v156
	v_lshlrev_b32_e32 v143, 1, v142
	v_lshlrev_b32_e32 v142, 2, v142
	v_lshlrev_b32_e32 v144, 2, v156
	v_lshrrev_b32_e32 v32, 6, v156
	s_nop 1
	v_readfirstlane_b32 s17, v32
	s_mov_b32 s10, 0x3fb8aa3b
	s_mov_b32 s11, 0xbfb8aa3b
	s_mov_b32 s12, 0x3f317218
	s_mov_b32 s13, 0x3d800000
	s_bfe_u32 s18, s88, 0x20001
	s_bitcmp1_b32 s88, 0
	s_cbranch_scc1 .Lpre_g_init
.Lpre_h_loop:
	s_lshr_b32 s19, s16, 3
	s_lshr_b32 s4, s17, 1
	s_lshl_b32 s4, s4, 5
	s_mov_b32 s23, 1
	s_cmp_lt_u32 s19, 0x400
	s_cbranch_scc1 .Lpre_h_full
	s_sub_u32 s20, s19, 0x400
	s_lshl_b32 s20, s20, 5
	s_add_u32 s20, s20, 0x10000
	s_add_u32 s20, s20, s4
	s_cmp_lt_u32 s4, 32
	s_cbranch_scc1 .Lpre_h_go
	s_mov_b32 s23, 0
	v_mov_b32_e32 v145, 0
	s_branch .Lpre_h_exch
.Lpre_h_full:
	s_lshl_b32 s20, s19, 6
	s_add_u32 s20, s20, s4
.Lpre_h_go:
	s_lshl_b32 s21, s20, 11
	s_lshl_b32 s4, s18, 9
	s_add_u32 s21, s21, s4
	s_add_u32 s22, s21, 0xc180000
	s_add_u32 s24, s94, s22
	s_addc_u32 s25, s95, 0
	s_lshl_b32 s21, s20, 10
	s_lshl_b32 s4, s18, 8
	s_add_u32 s21, s21, s4
	s_add_u32 s22, s21, 0x8100000
	s_add_u32 s26, s94, s22
	s_addc_u32 s27, s95, 0
	s_mov_b64 s[28:29], s[26:27]
	s_add_u32 s22, s21, 0x2a540000
	s_add_u32 s30, s94, s22
	s_addc_u32 s31, s95, 0
	s_waitcnt vmcnt(24)
	global_load_dword v64, v140, s[24:25]
	global_load_dword v65, v140, s[24:25] offset:2048
	s_add_u32 s24, s24, 0x1000
	s_addc_u32 s25, s25, 0
	global_load_dword v66, v140, s[24:25]
	global_load_dword v67, v140, s[24:25] offset:2048
	s_add_u32 s24, s24, 0x1000
	s_addc_u32 s25, s25, 0
	global_load_dword v68, v140, s[24:25]
	global_load_dword v69, v140, s[24:25] offset:2048
	s_add_u32 s24, s24, 0x1000
	s_addc_u32 s25, s25, 0
	global_load_dword v70, v140, s[24:25]
	global_load_dword v71, v140, s[24:25] offset:2048
	s_add_u32 s24, s24, 0x1000
	s_addc_u32 s25, s25, 0
	global_load_dword v72, v140, s[24:25]
	global_load_dword v73, v140, s[24:25] offset:2048
	s_add_u32 s24, s24, 0x1000
	s_addc_u32 s25, s25, 0
	global_load_dword v74, v140, s[24:25]
	global_load_dword v75, v140, s[24:25] offset:2048
	s_add_u32 s24, s24, 0x1000
	s_addc_u32 s25, s25, 0
	global_load_dword v76, v140, s[24:25]
	global_load_dword v77, v140, s[24:25] offset:2048
	s_add_u32 s24, s24, 0x1000
	s_addc_u32 s25, s25, 0
	global_load_dword v78, v140, s[24:25]
	global_load_dword v79, v140, s[24:25] offset:2048
	s_add_u32 s24, s24, 0x1000
	s_addc_u32 s25, s25, 0
	global_load_dword v80, v140, s[24:25]
	global_load_dword v81, v140, s[24:25] offset:2048
	s_add_u32 s24, s24, 0x1000
	s_addc_u32 s25, s25, 0
	global_load_dword v82, v140, s[24:25]
	global_load_dword v83, v140, s[24:25] offset:2048
	s_add_u32 s24, s24, 0x1000
	s_addc_u32 s25, s25, 0
	global_load_dword v84, v140, s[24:25]
	global_load_dword v85, v140, s[24:25] offset:2048
	s_add_u32 s24, s24, 0x1000
	s_addc_u32 s25, s25, 0
	global_load_dword v86, v140, s[24:25]
	global_load_dword v87, v140, s[24:25] offset:2048
	s_add_u32 s24, s24, 0x1000
	s_addc_u32 s25, s25, 0
	global_load_dword v88, v140, s[24:25]
	global_load_dword v89, v140, s[24:25] offset:2048
	s_add_u32 s24, s24, 0x1000
	s_addc_u32 s25, s25, 0
	global_load_dword v90, v140, s[24:25]
	global_load_dword v91, v140, s[24:25] offset:2048
	s_add_u32 s24, s24, 0x1000
	s_addc_u32 s25, s25, 0
	global_load_dword v92, v140, s[24:25]
	global_load_dword v93, v140, s[24:25] offset:2048
	s_add_u32 s24, s24, 0x1000
	s_addc_u32 s25, s25, 0
	global_load_dword v94, v140, s[24:25]
	global_load_dword v95, v140, s[24:25] offset:2048
	v_mov_b32_e32 v145, 0
	s_waitcnt vmcnt(28)
	v_log_f32_e32 v96, v64
	v_log_f32_e32 v97, v65
	v_log_f32_e32 v98, v66
	v_log_f32_e32 v99, v67
	v_sub_f32_e32 v64, 1.0, v64
	v_sub_f32_e32 v65, 1.0, v65
	v_sub_f32_e32 v66, 1.0, v66
	v_sub_f32_e32 v67, 1.0, v67
	v_mul_f32_e32 v96, s12, v96
	v_mul_f32_e32 v97, s12, v97
	v_mul_f32_e32 v98, s12, v98
	v_mul_f32_e32 v99, s12, v99
	v_add_f32_e32 v145, v145, v96
	v_add_f32_e32 v145, v145, v97
	v_add_f32_e32 v145, v145, v98
	v_add_f32_e32 v145, v145, v99
	s_waitcnt vmcnt(24)
	v_log_f32_e32 v100, v68
	v_log_f32_e32 v101, v69
	v_log_f32_e32 v102, v70
	v_log_f32_e32 v103, v71
	v_sub_f32_e32 v68, 1.0, v68
	v_sub_f32_e32 v69, 1.0, v69
	v_sub_f32_e32 v70, 1.0, v70
	v_sub_f32_e32 v71, 1.0, v71
	v_mul_f32_e32 v100, s12, v100
	v_mul_f32_e32 v101, s12, v101
	v_mul_f32_e32 v102, s12, v102
	v_mul_f32_e32 v103, s12, v103
	v_add_f32_e32 v145, v145, v100
	v_add_f32_e32 v145, v145, v101
	v_add_f32_e32 v145, v145, v102
	v_add_f32_e32 v145, v145, v103
	s_waitcnt vmcnt(20)
	v_log_f32_e32 v104, v72
	v_log_f32_e32 v105, v73
	v_log_f32_e32 v106, v74
	v_log_f32_e32 v107, v75
	v_sub_f32_e32 v72, 1.0, v72
	v_sub_f32_e32 v73, 1.0, v73
	v_sub_f32_e32 v74, 1.0, v74
	v_sub_f32_e32 v75, 1.0, v75
	v_mul_f32_e32 v104, s12, v104
	v_mul_f32_e32 v105, s12, v105
	v_mul_f32_e32 v106, s12, v106
	v_mul_f32_e32 v107, s12, v107
	v_add_f32_e32 v145, v145, v104
	v_add_f32_e32 v145, v145, v105
	v_add_f32_e32 v145, v145, v106
	v_add_f32_e32 v145, v145, v107
	s_waitcnt vmcnt(16)
	v_log_f32_e32 v108, v76
	v_log_f32_e32 v109, v77
	v_log_f32_e32 v110, v78
	v_log_f32_e32 v111, v79
	v_sub_f32_e32 v76, 1.0, v76
	v_sub_f32_e32 v77, 1.0, v77
	v_sub_f32_e32 v78, 1.0, v78
	v_sub_f32_e32 v79, 1.0, v79
	v_mul_f32_e32 v108, s12, v108
	v_mul_f32_e32 v109, s12, v109
	v_mul_f32_e32 v110, s12, v110
	v_mul_f32_e32 v111, s12, v111
	v_add_f32_e32 v145, v145, v108
	v_add_f32_e32 v145, v145, v109
	v_add_f32_e32 v145, v145, v110
	v_add_f32_e32 v145, v145, v111
	s_waitcnt vmcnt(12)
	v_log_f32_e32 v112, v80
	v_log_f32_e32 v113, v81
	v_log_f32_e32 v114, v82
	v_log_f32_e32 v115, v83
	v_sub_f32_e32 v80, 1.0, v80
	v_sub_f32_e32 v81, 1.0, v81
	v_sub_f32_e32 v82, 1.0, v82
	v_sub_f32_e32 v83, 1.0, v83
	v_mul_f32_e32 v112, s12, v112
	v_mul_f32_e32 v113, s12, v113
	v_mul_f32_e32 v114, s12, v114
	v_mul_f32_e32 v115, s12, v115
	v_add_f32_e32 v145, v145, v112
	v_add_f32_e32 v145, v145, v113
	v_add_f32_e32 v145, v145, v114
	v_add_f32_e32 v145, v145, v115
	s_waitcnt vmcnt(8)
	v_log_f32_e32 v116, v84
	v_log_f32_e32 v117, v85
	v_log_f32_e32 v118, v86
	v_log_f32_e32 v119, v87
	v_sub_f32_e32 v84, 1.0, v84
	v_sub_f32_e32 v85, 1.0, v85
	v_sub_f32_e32 v86, 1.0, v86
	v_sub_f32_e32 v87, 1.0, v87
	v_mul_f32_e32 v116, s12, v116
	v_mul_f32_e32 v117, s12, v117
	v_mul_f32_e32 v118, s12, v118
	v_mul_f32_e32 v119, s12, v119
	v_add_f32_e32 v145, v145, v116
	v_add_f32_e32 v145, v145, v117
	v_add_f32_e32 v145, v145, v118
	v_add_f32_e32 v145, v145, v119
	s_waitcnt vmcnt(4)
	v_log_f32_e32 v120, v88
	v_log_f32_e32 v121, v89
	v_log_f32_e32 v122, v90
	v_log_f32_e32 v123, v91
	v_sub_f32_e32 v88, 1.0, v88
	v_sub_f32_e32 v89, 1.0, v89
	v_sub_f32_e32 v90, 1.0, v90
	v_sub_f32_e32 v91, 1.0, v91
	v_mul_f32_e32 v120, s12, v120
	v_mul_f32_e32 v121, s12, v121
	v_mul_f32_e32 v122, s12, v122
	v_mul_f32_e32 v123, s12, v123
	v_add_f32_e32 v145, v145, v120
	v_add_f32_e32 v145, v145, v121
	v_add_f32_e32 v145, v145, v122
	v_add_f32_e32 v145, v145, v123
	s_waitcnt vmcnt(0)
	v_log_f32_e32 v124, v92
	v_log_f32_e32 v125, v93
	v_log_f32_e32 v126, v94
	v_log_f32_e32 v127, v95
	v_sub_f32_e32 v92, 1.0, v92
	v_sub_f32_e32 v93, 1.0, v93
	v_sub_f32_e32 v94, 1.0, v94
	v_sub_f32_e32 v95, 1.0, v95
	v_mul_f32_e32 v124, s12, v124
	v_mul_f32_e32 v125, s12, v125
	v_mul_f32_e32 v126, s12, v126
	v_mul_f32_e32 v127, s12, v127
	v_add_f32_e32 v145, v145, v124
	v_add_f32_e32 v145, v145, v125
	v_add_f32_e32 v145, v145, v126
	v_add_f32_e32 v145, v145, v127
	global_load_ushort v0, v141, s[26:27]
	global_load_ushort v1, v141, s[26:27] offset:1024
	global_load_ushort v2, v141, s[26:27] offset:2048
	global_load_ushort v3, v141, s[26:27] offset:3072
	s_add_u32 s26, s26, 0x1000
	s_addc_u32 s27, s27, 0
	global_load_ushort v4, v141, s[26:27]
	global_load_ushort v5, v141, s[26:27] offset:1024
	global_load_ushort v6, v141, s[26:27] offset:2048
	global_load_ushort v7, v141, s[26:27] offset:3072
	s_add_u32 s26, s26, 0x1000
	s_addc_u32 s27, s27, 0
	global_load_ushort v8, v141, s[26:27]
	global_load_ushort v9, v141, s[26:27] offset:1024
	global_load_ushort v10, v141, s[26:27] offset:2048
	global_load_ushort v11, v141, s[26:27] offset:3072
	s_add_u32 s26, s26, 0x1000
	s_addc_u32 s27, s27, 0
	global_load_ushort v12, v141, s[26:27]
	global_load_ushort v13, v141, s[26:27] offset:1024
	global_load_ushort v14, v141, s[26:27] offset:2048
	global_load_ushort v15, v141, s[26:27] offset:3072
	s_add_u32 s26, s26, 0x1000
	s_addc_u32 s27, s27, 0
	global_load_ushort v16, v141, s[26:27]
	global_load_ushort v17, v141, s[26:27] offset:1024
	global_load_ushort v18, v141, s[26:27] offset:2048
	global_load_ushort v19, v141, s[26:27] offset:3072
	s_add_u32 s26, s26, 0x1000
	s_addc_u32 s27, s27, 0
	global_load_ushort v20, v141, s[26:27]
	global_load_ushort v21, v141, s[26:27] offset:1024
	global_load_ushort v22, v141, s[26:27] offset:2048
	global_load_ushort v23, v141, s[26:27] offset:3072
	s_add_u32 s26, s26, 0x1000
	s_addc_u32 s27, s27, 0
	global_load_ushort v24, v141, s[26:27]
	global_load_ushort v25, v141, s[26:27] offset:1024
	global_load_ushort v26, v141, s[26:27] offset:2048
	global_load_ushort v27, v141, s[26:27] offset:3072
	s_add_u32 s26, s26, 0x1000
	s_addc_u32 s27, s27, 0
	global_load_ushort v28, v141, s[26:27]
	global_load_ushort v29, v141, s[26:27] offset:1024
	global_load_ushort v30, v141, s[26:27] offset:2048
	global_load_ushort v31, v141, s[26:27] offset:3072
.Lpre_h_exch:
	s_barrier
	ds_write_b32 v144, v145
	s_waitcnt lgkmcnt(0)
	s_barrier
	ds_read_b32 v132, v140
	ds_read_b32 v133, v140 offset:512
	s_waitcnt lgkmcnt(0)
	v_add_f32_e32 v136, v132, v133
	v_mov_b32_e32 v145, 0
	s_cmp_lt_u32 s17, 2
	s_cbranch_scc0 .Lpre_h_tp1
	s_mul_i32 s21, s19, 0xc00
	s_lshl_b32 s4, s18, 9
	s_add_u32 s21, s21, s4
	s_add_u32 s22, s21, 0x28d00000
	s_add_u32 s34, s94, s22
	s_addc_u32 s35, s95, 0
	v_mul_f32_e32 v32, s10, v136
	v_exp_f32_e32 v32, v32
	s_nop 0
	global_store_dword v140, v32, s[34:35]
	s_branch .Lpre_h_p2
.Lpre_h_tp1:
	v_mov_b32_e32 v145, v132
.Lpre_h_p2:
	s_cmp_eq_u32 s23, 0
	s_cbranch_scc1 .Lpre_h_next
	s_waitcnt vmcnt(0)
	v_add_f32_e32 v32, v145, v96
	v_add_f32_e32 v33, v32, v97
	v_add_f32_e32 v34, v33, v98
	v_add_f32_e32 v35, v34, v99
	v_mov_b32_e32 v145, v35
	v_mul_f32_e32 v32, s10, v32
	v_mul_f32_e32 v33, s10, v33
	v_mul_f32_e32 v34, s10, v34
	v_mul_f32_e32 v35, s10, v35
	v_exp_f32_e32 v36, v32
	v_exp_f32_e32 v37, v33
	v_exp_f32_e32 v38, v34
	v_exp_f32_e32 v39, v35
	v_exp_f32_e64 v40, -v32
	v_exp_f32_e64 v41, -v33
	v_exp_f32_e64 v42, -v34
	v_exp_f32_e64 v43, -v35
	v_lshlrev_b32_e32 v44, 16, v0
	v_lshlrev_b32_e32 v45, 16, v1
	v_lshlrev_b32_e32 v46, 16, v2
	v_lshlrev_b32_e32 v47, 16, v3
	v_mul_f32_e32 v36, v44, v36
	v_mul_f32_e32 v37, v45, v37
	v_mul_f32_e32 v38, v46, v38
	v_mul_f32_e32 v39, v47, v39
	v_mul_f32_e32 v40, v64, v40
	v_mul_f32_e32 v41, v65, v41
	v_mul_f32_e32 v42, v66, v42
	v_mul_f32_e32 v43, v67, v43
	v_cvt_pk_bf16_f32 v44, v36, v40
	v_cvt_pk_bf16_f32 v45, v37, v41
	v_cvt_pk_bf16_f32 v46, v38, v42
	v_cvt_pk_bf16_f32 v47, v39, v43
	s_nop 0
	global_store_short v141, v44, s[28:29]
	global_store_short_d16_hi v141, v44, s[30:31]
	global_store_short v141, v45, s[28:29] offset:1024
	global_store_short_d16_hi v141, v45, s[30:31] offset:1024
	global_store_short v141, v46, s[28:29] offset:2048
	global_store_short_d16_hi v141, v46, s[30:31] offset:2048
	global_store_short v141, v47, s[28:29] offset:3072
	global_store_short_d16_hi v141, v47, s[30:31] offset:3072
	s_add_u32 s28, s28, 0x1000
	s_addc_u32 s29, s29, 0
	s_add_u32 s30, s30, 0x1000
	s_addc_u32 s31, s31, 0
	v_add_f32_e32 v32, v145, v100
	v_add_f32_e32 v33, v32, v101
	v_add_f32_e32 v34, v33, v102
	v_add_f32_e32 v35, v34, v103
	v_mov_b32_e32 v145, v35
	v_mul_f32_e32 v32, s10, v32
	v_mul_f32_e32 v33, s10, v33
	v_mul_f32_e32 v34, s10, v34
	v_mul_f32_e32 v35, s10, v35
	v_exp_f32_e32 v36, v32
	v_exp_f32_e32 v37, v33
	v_exp_f32_e32 v38, v34
	v_exp_f32_e32 v39, v35
	v_exp_f32_e64 v40, -v32
	v_exp_f32_e64 v41, -v33
	v_exp_f32_e64 v42, -v34
	v_exp_f32_e64 v43, -v35
	v_lshlrev_b32_e32 v44, 16, v4
	v_lshlrev_b32_e32 v45, 16, v5
	v_lshlrev_b32_e32 v46, 16, v6
	v_lshlrev_b32_e32 v47, 16, v7
	v_mul_f32_e32 v36, v44, v36
	v_mul_f32_e32 v37, v45, v37
	v_mul_f32_e32 v38, v46, v38
	v_mul_f32_e32 v39, v47, v39
	v_mul_f32_e32 v40, v68, v40
	v_mul_f32_e32 v41, v69, v41
	v_mul_f32_e32 v42, v70, v42
	v_mul_f32_e32 v43, v71, v43
	v_cvt_pk_bf16_f32 v44, v36, v40
	v_cvt_pk_bf16_f32 v45, v37, v41
	v_cvt_pk_bf16_f32 v46, v38, v42
	v_cvt_pk_bf16_f32 v47, v39, v43
	s_nop 0
	global_store_short v141, v44, s[28:29]
	global_store_short_d16_hi v141, v44, s[30:31]
	global_store_short v141, v45, s[28:29] offset:1024
	global_store_short_d16_hi v141, v45, s[30:31] offset:1024
	global_store_short v141, v46, s[28:29] offset:2048
	global_store_short_d16_hi v141, v46, s[30:31] offset:2048
	global_store_short v141, v47, s[28:29] offset:3072
	global_store_short_d16_hi v141, v47, s[30:31] offset:3072
	s_add_u32 s28, s28, 0x1000
	s_addc_u32 s29, s29, 0
	s_add_u32 s30, s30, 0x1000
	s_addc_u32 s31, s31, 0
	v_add_f32_e32 v32, v145, v104
	v_add_f32_e32 v33, v32, v105
	v_add_f32_e32 v34, v33, v106
	v_add_f32_e32 v35, v34, v107
	v_mov_b32_e32 v145, v35
	v_mul_f32_e32 v32, s10, v32
	v_mul_f32_e32 v33, s10, v33
	v_mul_f32_e32 v34, s10, v34
	v_mul_f32_e32 v35, s10, v35
	v_exp_f32_e32 v36, v32
	v_exp_f32_e32 v37, v33
	v_exp_f32_e32 v38, v34
	v_exp_f32_e32 v39, v35
	v_exp_f32_e64 v40, -v32
	v_exp_f32_e64 v41, -v33
	v_exp_f32_e64 v42, -v34
	v_exp_f32_e64 v43, -v35
	v_lshlrev_b32_e32 v44, 16, v8
	v_lshlrev_b32_e32 v45, 16, v9
	v_lshlrev_b32_e32 v46, 16, v10
	v_lshlrev_b32_e32 v47, 16, v11
	v_mul_f32_e32 v36, v44, v36
	v_mul_f32_e32 v37, v45, v37
	v_mul_f32_e32 v38, v46, v38
	v_mul_f32_e32 v39, v47, v39
	v_mul_f32_e32 v40, v72, v40
	v_mul_f32_e32 v41, v73, v41
	v_mul_f32_e32 v42, v74, v42
	v_mul_f32_e32 v43, v75, v43
	v_cvt_pk_bf16_f32 v44, v36, v40
	v_cvt_pk_bf16_f32 v45, v37, v41
	v_cvt_pk_bf16_f32 v46, v38, v42
	v_cvt_pk_bf16_f32 v47, v39, v43
	s_nop 0
	global_store_short v141, v44, s[28:29]
	global_store_short_d16_hi v141, v44, s[30:31]
	global_store_short v141, v45, s[28:29] offset:1024
	global_store_short_d16_hi v141, v45, s[30:31] offset:1024
	global_store_short v141, v46, s[28:29] offset:2048
	global_store_short_d16_hi v141, v46, s[30:31] offset:2048
	global_store_short v141, v47, s[28:29] offset:3072
	global_store_short_d16_hi v141, v47, s[30:31] offset:3072
	s_add_u32 s28, s28, 0x1000
	s_addc_u32 s29, s29, 0
	s_add_u32 s30, s30, 0x1000
	s_addc_u32 s31, s31, 0
	v_add_f32_e32 v32, v145, v108
	v_add_f32_e32 v33, v32, v109
	v_add_f32_e32 v34, v33, v110
	v_add_f32_e32 v35, v34, v111
	v_mov_b32_e32 v145, v35
	v_mul_f32_e32 v32, s10, v32
	v_mul_f32_e32 v33, s10, v33
	v_mul_f32_e32 v34, s10, v34
	v_mul_f32_e32 v35, s10, v35
	v_exp_f32_e32 v36, v32
	v_exp_f32_e32 v37, v33
	v_exp_f32_e32 v38, v34
	v_exp_f32_e32 v39, v35
	v_exp_f32_e64 v40, -v32
	v_exp_f32_e64 v41, -v33
	v_exp_f32_e64 v42, -v34
	v_exp_f32_e64 v43, -v35
	v_lshlrev_b32_e32 v44, 16, v12
	v_lshlrev_b32_e32 v45, 16, v13
	v_lshlrev_b32_e32 v46, 16, v14
	v_lshlrev_b32_e32 v47, 16, v15
	v_mul_f32_e32 v36, v44, v36
	v_mul_f32_e32 v37, v45, v37
	v_mul_f32_e32 v38, v46, v38
	v_mul_f32_e32 v39, v47, v39
	v_mul_f32_e32 v40, v76, v40
	v_mul_f32_e32 v41, v77, v41
	v_mul_f32_e32 v42, v78, v42
	v_mul_f32_e32 v43, v79, v43
	v_cvt_pk_bf16_f32 v44, v36, v40
	v_cvt_pk_bf16_f32 v45, v37, v41
	v_cvt_pk_bf16_f32 v46, v38, v42
	v_cvt_pk_bf16_f32 v47, v39, v43
	s_nop 0
	global_store_short v141, v44, s[28:29]
	global_store_short_d16_hi v141, v44, s[30:31]
	global_store_short v141, v45, s[28:29] offset:1024
	global_store_short_d16_hi v141, v45, s[30:31] offset:1024
	global_store_short v141, v46, s[28:29] offset:2048
	global_store_short_d16_hi v141, v46, s[30:31] offset:2048
	global_store_short v141, v47, s[28:29] offset:3072
	global_store_short_d16_hi v141, v47, s[30:31] offset:3072
	s_add_u32 s28, s28, 0x1000
	s_addc_u32 s29, s29, 0
	s_add_u32 s30, s30, 0x1000
	s_addc_u32 s31, s31, 0
	v_add_f32_e32 v32, v145, v112
	v_add_f32_e32 v33, v32, v113
	v_add_f32_e32 v34, v33, v114
	v_add_f32_e32 v35, v34, v115
	v_mov_b32_e32 v145, v35
	v_mul_f32_e32 v32, s10, v32
	v_mul_f32_e32 v33, s10, v33
	v_mul_f32_e32 v34, s10, v34
	v_mul_f32_e32 v35, s10, v35
	v_exp_f32_e32 v36, v32
	v_exp_f32_e32 v37, v33
	v_exp_f32_e32 v38, v34
	v_exp_f32_e32 v39, v35
	v_exp_f32_e64 v40, -v32
	v_exp_f32_e64 v41, -v33
	v_exp_f32_e64 v42, -v34
	v_exp_f32_e64 v43, -v35
	v_lshlrev_b32_e32 v44, 16, v16
	v_lshlrev_b32_e32 v45, 16, v17
	v_lshlrev_b32_e32 v46, 16, v18
	v_lshlrev_b32_e32 v47, 16, v19
	v_mul_f32_e32 v36, v44, v36
	v_mul_f32_e32 v37, v45, v37
	v_mul_f32_e32 v38, v46, v38
	v_mul_f32_e32 v39, v47, v39
	v_mul_f32_e32 v40, v80, v40
	v_mul_f32_e32 v41, v81, v41
	v_mul_f32_e32 v42, v82, v42
	v_mul_f32_e32 v43, v83, v43
	v_cvt_pk_bf16_f32 v44, v36, v40
	v_cvt_pk_bf16_f32 v45, v37, v41
	v_cvt_pk_bf16_f32 v46, v38, v42
	v_cvt_pk_bf16_f32 v47, v39, v43
	s_nop 0
	global_store_short v141, v44, s[28:29]
	global_store_short_d16_hi v141, v44, s[30:31]
	global_store_short v141, v45, s[28:29] offset:1024
	global_store_short_d16_hi v141, v45, s[30:31] offset:1024
	global_store_short v141, v46, s[28:29] offset:2048
	global_store_short_d16_hi v141, v46, s[30:31] offset:2048
	global_store_short v141, v47, s[28:29] offset:3072
	global_store_short_d16_hi v141, v47, s[30:31] offset:3072
	s_add_u32 s28, s28, 0x1000
	s_addc_u32 s29, s29, 0
	s_add_u32 s30, s30, 0x1000
	s_addc_u32 s31, s31, 0
	v_add_f32_e32 v32, v145, v116
	v_add_f32_e32 v33, v32, v117
	v_add_f32_e32 v34, v33, v118
	v_add_f32_e32 v35, v34, v119
	v_mov_b32_e32 v145, v35
	v_mul_f32_e32 v32, s10, v32
	v_mul_f32_e32 v33, s10, v33
	v_mul_f32_e32 v34, s10, v34
	v_mul_f32_e32 v35, s10, v35
	v_exp_f32_e32 v36, v32
	v_exp_f32_e32 v37, v33
	v_exp_f32_e32 v38, v34
	v_exp_f32_e32 v39, v35
	v_exp_f32_e64 v40, -v32
	v_exp_f32_e64 v41, -v33
	v_exp_f32_e64 v42, -v34
	v_exp_f32_e64 v43, -v35
	v_lshlrev_b32_e32 v44, 16, v20
	v_lshlrev_b32_e32 v45, 16, v21
	v_lshlrev_b32_e32 v46, 16, v22
	v_lshlrev_b32_e32 v47, 16, v23
	v_mul_f32_e32 v36, v44, v36
	v_mul_f32_e32 v37, v45, v37
	v_mul_f32_e32 v38, v46, v38
	v_mul_f32_e32 v39, v47, v39
	v_mul_f32_e32 v40, v84, v40
	v_mul_f32_e32 v41, v85, v41
	v_mul_f32_e32 v42, v86, v42
	v_mul_f32_e32 v43, v87, v43
	v_cvt_pk_bf16_f32 v44, v36, v40
	v_cvt_pk_bf16_f32 v45, v37, v41
	v_cvt_pk_bf16_f32 v46, v38, v42
	v_cvt_pk_bf16_f32 v47, v39, v43
	s_nop 0
	global_store_short v141, v44, s[28:29]
	global_store_short_d16_hi v141, v44, s[30:31]
	global_store_short v141, v45, s[28:29] offset:1024
	global_store_short_d16_hi v141, v45, s[30:31] offset:1024
	global_store_short v141, v46, s[28:29] offset:2048
	global_store_short_d16_hi v141, v46, s[30:31] offset:2048
	global_store_short v141, v47, s[28:29] offset:3072
	global_store_short_d16_hi v141, v47, s[30:31] offset:3072
	s_add_u32 s28, s28, 0x1000
	s_addc_u32 s29, s29, 0
	s_add_u32 s30, s30, 0x1000
	s_addc_u32 s31, s31, 0
	v_add_f32_e32 v32, v145, v120
	v_add_f32_e32 v33, v32, v121
	v_add_f32_e32 v34, v33, v122
	v_add_f32_e32 v35, v34, v123
	v_mov_b32_e32 v145, v35
	v_mul_f32_e32 v32, s10, v32
	v_mul_f32_e32 v33, s10, v33
	v_mul_f32_e32 v34, s10, v34
	v_mul_f32_e32 v35, s10, v35
	v_exp_f32_e32 v36, v32
	v_exp_f32_e32 v37, v33
	v_exp_f32_e32 v38, v34
	v_exp_f32_e32 v39, v35
	v_exp_f32_e64 v40, -v32
	v_exp_f32_e64 v41, -v33
	v_exp_f32_e64 v42, -v34
	v_exp_f32_e64 v43, -v35
	v_lshlrev_b32_e32 v44, 16, v24
	v_lshlrev_b32_e32 v45, 16, v25
	v_lshlrev_b32_e32 v46, 16, v26
	v_lshlrev_b32_e32 v47, 16, v27
	v_mul_f32_e32 v36, v44, v36
	v_mul_f32_e32 v37, v45, v37
	v_mul_f32_e32 v38, v46, v38
	v_mul_f32_e32 v39, v47, v39
	v_mul_f32_e32 v40, v88, v40
	v_mul_f32_e32 v41, v89, v41
	v_mul_f32_e32 v42, v90, v42
	v_mul_f32_e32 v43, v91, v43
	v_cvt_pk_bf16_f32 v44, v36, v40
	v_cvt_pk_bf16_f32 v45, v37, v41
	v_cvt_pk_bf16_f32 v46, v38, v42
	v_cvt_pk_bf16_f32 v47, v39, v43
	s_nop 0
	global_store_short v141, v44, s[28:29]
	global_store_short_d16_hi v141, v44, s[30:31]
	global_store_short v141, v45, s[28:29] offset:1024
	global_store_short_d16_hi v141, v45, s[30:31] offset:1024
	global_store_short v141, v46, s[28:29] offset:2048
	global_store_short_d16_hi v141, v46, s[30:31] offset:2048
	global_store_short v141, v47, s[28:29] offset:3072
	global_store_short_d16_hi v141, v47, s[30:31] offset:3072
	s_add_u32 s28, s28, 0x1000
	s_addc_u32 s29, s29, 0
	s_add_u32 s30, s30, 0x1000
	s_addc_u32 s31, s31, 0
	v_add_f32_e32 v32, v145, v124
	v_add_f32_e32 v33, v32, v125
	v_add_f32_e32 v34, v33, v126
	v_add_f32_e32 v35, v34, v127
	v_mov_b32_e32 v145, v35
	v_mul_f32_e32 v32, s10, v32
	v_mul_f32_e32 v33, s10, v33
	v_mul_f32_e32 v34, s10, v34
	v_mul_f32_e32 v35, s10, v35
	v_exp_f32_e32 v36, v32
	v_exp_f32_e32 v37, v33
	v_exp_f32_e32 v38, v34
	v_exp_f32_e32 v39, v35
	v_exp_f32_e64 v40, -v32
	v_exp_f32_e64 v41, -v33
	v_exp_f32_e64 v42, -v34
	v_exp_f32_e64 v43, -v35
	v_lshlrev_b32_e32 v44, 16, v28
	v_lshlrev_b32_e32 v45, 16, v29
	v_lshlrev_b32_e32 v46, 16, v30
	v_lshlrev_b32_e32 v47, 16, v31
	v_mul_f32_e32 v36, v44, v36
	v_mul_f32_e32 v37, v45, v37
	v_mul_f32_e32 v38, v46, v38
	v_mul_f32_e32 v39, v47, v39
	v_mul_f32_e32 v40, v92, v40
	v_mul_f32_e32 v41, v93, v41
	v_mul_f32_e32 v42, v94, v42
	v_mul_f32_e32 v43, v95, v43
	v_cvt_pk_bf16_f32 v44, v36, v40
	v_cvt_pk_bf16_f32 v45, v37, v41
	v_cvt_pk_bf16_f32 v46, v38, v42
	v_cvt_pk_bf16_f32 v47, v39, v43
	s_nop 0
	global_store_short v141, v44, s[28:29]
	global_store_short_d16_hi v141, v44, s[30:31]
	global_store_short v141, v45, s[28:29] offset:1024
	global_store_short_d16_hi v141, v45, s[30:31] offset:1024
	global_store_short v141, v46, s[28:29] offset:2048
	global_store_short_d16_hi v141, v46, s[30:31] offset:2048
	global_store_short v141, v47, s[28:29] offset:3072
	global_store_short_d16_hi v141, v47, s[30:31] offset:3072
.Lpre_h_next:
	s_add_i32 s16, s16, s96
	s_cmpk_lt_i32 s16, 0x2080
	s_cbranch_scc1 .Lpre_h_loop
	s_branch .LBB0_377
.Lpre_g_init:
	v_readlane_b32 s36, v253, 28
	v_readlane_b32 s37, v253, 29
	v_readlane_b32 s34, v253, 30
	v_readlane_b32 s35, v253, 31
	s_nop 3
	s_lshl_b32 s4, s18, 8
	s_add_u32 s36, s36, s4
	s_addc_u32 s37, s37, 0
	s_add_u32 s34, s34, s4
	s_addc_u32 s35, s35, 0
	s_nop 3
	global_load_dword v80, v142, s[34:35]
	global_load_dword v64, v142, s[36:37]
	global_load_dword v65, v142, s[36:37] offset:1024
	global_load_dword v66, v142, s[36:37] offset:2048
	global_load_dword v67, v142, s[36:37] offset:3072
	s_add_u32 s36, s36, 0x1000
	s_addc_u32 s37, s37, 0
	global_load_dword v68, v142, s[36:37]
	global_load_dword v69, v142, s[36:37] offset:1024
	global_load_dword v70, v142, s[36:37] offset:2048
	global_load_dword v71, v142, s[36:37] offset:3072
	s_add_u32 s36, s36, 0x1000
	s_addc_u32 s37, s37, 0
	global_load_dword v72, v142, s[36:37]
	global_load_dword v73, v142, s[36:37] offset:1024
	global_load_dword v74, v142, s[36:37] offset:2048
	global_load_dword v75, v142, s[36:37] offset:3072
	s_add_u32 s36, s36, 0x1000
	s_addc_u32 s37, s37, 0
	global_load_dword v76, v142, s[36:37]
	global_load_dword v77, v142, s[36:37] offset:1024
	global_load_dword v78, v142, s[36:37] offset:2048
	global_load_dword v79, v142, s[36:37] offset:3072
.Lpre_g_loop:
	s_lshr_b32 s19, s16, 3
	s_lshl_b32 s4, s17, 4
	s_mov_b32 s23, 1
	s_cmp_lt_u32 s19, 0x400
	s_cbranch_scc1 .Lpre_g_full
	s_sub_u32 s20, s19, 0x400
	s_lshl_b32 s20, s20, 5
	s_add_u32 s20, s20, 0x10000
	s_add_u32 s20, s20, s4
	s_cmp_lt_u32 s4, 32
	s_cbranch_scc1 .Lpre_g_go
	s_mov_b32 s23, 0
	v_mov_b32_e32 v145, 0
	s_branch .Lpre_g_exch

.Lpre_g_go:
	s_lshl_b32 s21, s20, 6
	s_add_u32 s22, s21, 0x28500000
	s_add_u32 s24, s94, s22
	s_addc_u32 s25, s95, 0
	s_lshl_b32 s21, s20, 9
	s_lshl_b32 s4, s18, 7
	s_add_u32 s21, s21, s4
	s_add_u32 s22, s21, 0x1c380000
	s_add_u32 s26, s94, s22
	s_addc_u32 s27, s95, 0
	s_mov_b64 s[28:29], s[26:27]
	s_add_u32 s22, s21, 0x2e5c0000
	s_add_u32 s30, s94, s22
	s_addc_u32 s31, s95, 0
	s_add_u32 s22, s21, 0x1e3c0000
	s_add_u32 s34, s94, s22
	s_addc_u32 s35, s95, 0
	s_waitcnt vmcnt(24)
	s_load_dwordx16 s[40:55], s[24:25], 0x0 glc
	s_load_dwordx16 s[56:71], s[24:25], 0x40 glc
	s_load_dwordx16 s[72:87], s[24:25], 0x80 glc
	global_load_ushort v96, v143, s[34:35]
	global_load_ushort v97, v143, s[34:35] offset:512
	global_load_ushort v98, v143, s[34:35] offset:1024
	global_load_ushort v99, v143, s[34:35] offset:1536
	global_load_ushort v100, v143, s[34:35] offset:2048
	global_load_ushort v101, v143, s[34:35] offset:2560
	global_load_ushort v102, v143, s[34:35] offset:3072
	global_load_ushort v103, v143, s[34:35] offset:3584
	s_add_u32 s34, s34, 0x1000
	s_addc_u32 s35, s35, 0
	global_load_ushort v104, v143, s[34:35]
	global_load_ushort v105, v143, s[34:35] offset:512
	global_load_ushort v106, v143, s[34:35] offset:1024
	global_load_ushort v107, v143, s[34:35] offset:1536
	global_load_ushort v108, v143, s[34:35] offset:2048
	global_load_ushort v109, v143, s[34:35] offset:2560
	global_load_ushort v110, v143, s[34:35] offset:3072
	global_load_ushort v111, v143, s[34:35] offset:3584
	global_load_ushort v0, v143, s[26:27]
	global_load_ushort v1, v143, s[26:27] offset:512
	global_load_ushort v2, v143, s[26:27] offset:1024
	global_load_ushort v3, v143, s[26:27] offset:1536
	global_load_ushort v4, v143, s[26:27] offset:2048
	global_load_ushort v5, v143, s[26:27] offset:2560
	global_load_ushort v6, v143, s[26:27] offset:3072
	global_load_ushort v7, v143, s[26:27] offset:3584
	s_add_u32 s26, s26, 0x1000
	s_addc_u32 s27, s27, 0
	global_load_ushort v8, v143, s[26:27]
	global_load_ushort v9, v143, s[26:27] offset:512
	global_load_ushort v10, v143, s[26:27] offset:1024
	global_load_ushort v11, v143, s[26:27] offset:1536
	global_load_ushort v12, v143, s[26:27] offset:2048
	global_load_ushort v13, v143, s[26:27] offset:2560
	global_load_ushort v14, v143, s[26:27] offset:3072
	global_load_ushort v15, v143, s[26:27] offset:3584
	v_mov_b32_e32 v145, 0
	s_waitcnt vmcnt(32)
	s_waitcnt lgkmcnt(0)
	v_mov_b32_e32 v32, v80
	v_fmac_f32_e32 v32, s40, v64
	v_fmac_f32_e32 v32, s41, v65
	v_fmac_f32_e32 v32, s42, v66
	v_fmac_f32_e32 v32, s43, v67
	v_fmac_f32_e32 v32, s44, v68
	v_fmac_f32_e32 v32, s45, v69
	v_fmac_f32_e32 v32, s46, v70
	v_fmac_f32_e32 v32, s47, v71
	v_fmac_f32_e32 v32, s48, v72
	v_fmac_f32_e32 v32, s49, v73
	v_fmac_f32_e32 v32, s50, v74
	v_fmac_f32_e32 v32, s51, v75
	v_fmac_f32_e32 v32, s52, v76
	v_fmac_f32_e32 v32, s53, v77
	v_fmac_f32_e32 v32, s54, v78
	v_fmac_f32_e32 v32, s55, v79
	s_load_dwordx16 s[40:55], s[24:25], 0xc0 glc
	v_min_f32_e32 v33, 0, v32
	v_mul_f32_e64 v34, |v32|, s11
	v_exp_f32_e32 v34, v34
	s_nop 0
	v_add_f32_e32 v34, 1.0, v34
	v_log_f32_e32 v34, v34
	s_nop 0
	v_mul_f32_e32 v34, s12, v34
	v_sub_f32_e32 v33, v33, v34
	v_mul_f32_e32 v112, s13, v33
	v_add_f32_e32 v145, v145, v112
	s_waitcnt lgkmcnt(0)
	v_mov_b32_e32 v32, v80
	v_fmac_f32_e32 v32, s56, v64
	v_fmac_f32_e32 v32, s57, v65
	v_fmac_f32_e32 v32, s58, v66
	v_fmac_f32_e32 v32, s59, v67
	v_fmac_f32_e32 v32, s60, v68
	v_fmac_f32_e32 v32, s61, v69
	v_fmac_f32_e32 v32, s62, v70
	v_fmac_f32_e32 v32, s63, v71
	v_fmac_f32_e32 v32, s64, v72
	v_fmac_f32_e32 v32, s65, v73
	v_fmac_f32_e32 v32, s66, v74
	v_fmac_f32_e32 v32, s67, v75
	v_fmac_f32_e32 v32, s68, v76
	v_fmac_f32_e32 v32, s69, v77
	v_fmac_f32_e32 v32, s70, v78
	v_fmac_f32_e32 v32, s71, v79
	s_load_dwordx16 s[56:71], s[24:25], 0x100 glc
	v_min_f32_e32 v33, 0, v32
	v_mul_f32_e64 v34, |v32|, s11
	v_exp_f32_e32 v34, v34
	s_nop 0
	v_add_f32_e32 v34, 1.0, v34
	v_log_f32_e32 v34, v34
	s_nop 0
	v_mul_f32_e32 v34, s12, v34
	v_sub_f32_e32 v33, v33, v34
	v_mul_f32_e32 v113, s13, v33
	v_add_f32_e32 v145, v145, v113
	s_waitcnt lgkmcnt(0)
	v_mov_b32_e32 v32, v80
	v_fmac_f32_e32 v32, s72, v64
	v_fmac_f32_e32 v32, s73, v65
	v_fmac_f32_e32 v32, s74, v66
	v_fmac_f32_e32 v32, s75, v67
	v_fmac_f32_e32 v32, s76, v68
	v_fmac_f32_e32 v32, s77, v69
	v_fmac_f32_e32 v32, s78, v70
	v_fmac_f32_e32 v32, s79, v71
	v_fmac_f32_e32 v32, s80, v72
	v_fmac_f32_e32 v32, s81, v73
	v_fmac_f32_e32 v32, s82, v74
	v_fmac_f32_e32 v32, s83, v75
	v_fmac_f32_e32 v32, s84, v76
	v_fmac_f32_e32 v32, s85, v77
	v_fmac_f32_e32 v32, s86, v78
	v_fmac_f32_e32 v32, s87, v79
	s_load_dwordx16 s[72:87], s[24:25], 0x140 glc
	v_min_f32_e32 v33, 0, v32
	v_mul_f32_e64 v34, |v32|, s11
	v_exp_f32_e32 v34, v34
	s_nop 0
	v_add_f32_e32 v34, 1.0, v34
	v_log_f32_e32 v34, v34
	s_nop 0
	v_mul_f32_e32 v34, s12, v34
	v_sub_f32_e32 v33, v33, v34
	v_mul_f32_e32 v114, s13, v33
	v_add_f32_e32 v145, v145, v114
	s_waitcnt lgkmcnt(0)
	v_mov_b32_e32 v32, v80
	v_fmac_f32_e32 v32, s40, v64
	v_fmac_f32_e32 v32, s41, v65
	v_fmac_f32_e32 v32, s42, v66
	v_fmac_f32_e32 v32, s43, v67
	v_fmac_f32_e32 v32, s44, v68
	v_fmac_f32_e32 v32, s45, v69
	v_fmac_f32_e32 v32, s46, v70
	v_fmac_f32_e32 v32, s47, v71
	v_fmac_f32_e32 v32, s48, v72
	v_fmac_f32_e32 v32, s49, v73
	v_fmac_f32_e32 v32, s50, v74
	v_fmac_f32_e32 v32, s51, v75
	v_fmac_f32_e32 v32, s52, v76
	v_fmac_f32_e32 v32, s53, v77
	v_fmac_f32_e32 v32, s54, v78
	v_fmac_f32_e32 v32, s55, v79
	s_load_dwordx16 s[40:55], s[24:25], 0x180 glc
	v_min_f32_e32 v33, 0, v32
	v_mul_f32_e64 v34, |v32|, s11
	v_exp_f32_e32 v34, v34
	s_nop 0
	v_add_f32_e32 v34, 1.0, v34
	v_log_f32_e32 v34, v34
	s_nop 0
	v_mul_f32_e32 v34, s12, v34
	v_sub_f32_e32 v33, v33, v34
	v_mul_f32_e32 v115, s13, v33
	v_add_f32_e32 v145, v145, v115
	s_waitcnt lgkmcnt(0)
	v_mov_b32_e32 v32, v80
	v_fmac_f32_e32 v32, s56, v64
	v_fmac_f32_e32 v32, s57, v65
	v_fmac_f32_e32 v32, s58, v66
	v_fmac_f32_e32 v32, s59, v67
	v_fmac_f32_e32 v32, s60, v68
	v_fmac_f32_e32 v32, s61, v69
	v_fmac_f32_e32 v32, s62, v70
	v_fmac_f32_e32 v32, s63, v71
	v_fmac_f32_e32 v32, s64, v72
	v_fmac_f32_e32 v32, s65, v73
	v_fmac_f32_e32 v32, s66, v74
	v_fmac_f32_e32 v32, s67, v75
	v_fmac_f32_e32 v32, s68, v76
	v_fmac_f32_e32 v32, s69, v77
	v_fmac_f32_e32 v32, s70, v78
	v_fmac_f32_e32 v32, s71, v79
	s_load_dwordx16 s[56:71], s[24:25], 0x1c0 glc
	v_min_f32_e32 v33, 0, v32
	v_mul_f32_e64 v34, |v32|, s11
	v_exp_f32_e32 v34, v34
	s_nop 0
	v_add_f32_e32 v34, 1.0, v34
	v_log_f32_e32 v34, v34
	s_nop 0
	v_mul_f32_e32 v34, s12, v34
	v_sub_f32_e32 v33, v33, v34
	v_mul_f32_e32 v116, s13, v33
	v_add_f32_e32 v145, v145, v116
	s_waitcnt lgkmcnt(0)
	v_mov_b32_e32 v32, v80
	v_fmac_f32_e32 v32, s72, v64
	v_fmac_f32_e32 v32, s73, v65
	v_fmac_f32_e32 v32, s74, v66
	v_fmac_f32_e32 v32, s75, v67
	v_fmac_f32_e32 v32, s76, v68
	v_fmac_f32_e32 v32, s77, v69
	v_fmac_f32_e32 v32, s78, v70
	v_fmac_f32_e32 v32, s79, v71
	v_fmac_f32_e32 v32, s80, v72
	v_fmac_f32_e32 v32, s81, v73
	v_fmac_f32_e32 v32, s82, v74
	v_fmac_f32_e32 v32, s83, v75
	v_fmac_f32_e32 v32, s84, v76
	v_fmac_f32_e32 v32, s85, v77
	v_fmac_f32_e32 v32, s86, v78
	v_fmac_f32_e32 v32, s87, v79
	s_load_dwordx16 s[72:87], s[24:25], 0x200 glc
	v_min_f32_e32 v33, 0, v32
	v_mul_f32_e64 v34, |v32|, s11
	v_exp_f32_e32 v34, v34
	s_nop 0
	v_add_f32_e32 v34, 1.0, v34
	v_log_f32_e32 v34, v34
	s_nop 0
	v_mul_f32_e32 v34, s12, v34
	v_sub_f32_e32 v33, v33, v34
	v_mul_f32_e32 v117, s13, v33
	v_add_f32_e32 v145, v145, v117
	s_waitcnt lgkmcnt(0)
	v_mov_b32_e32 v32, v80
	v_fmac_f32_e32 v32, s40, v64
	v_fmac_f32_e32 v32, s41, v65
	v_fmac_f32_e32 v32, s42, v66
	v_fmac_f32_e32 v32, s43, v67
	v_fmac_f32_e32 v32, s44, v68
	v_fmac_f32_e32 v32, s45, v69
	v_fmac_f32_e32 v32, s46, v70
	v_fmac_f32_e32 v32, s47, v71
	v_fmac_f32_e32 v32, s48, v72
	v_fmac_f32_e32 v32, s49, v73
	v_fmac_f32_e32 v32, s50, v74
	v_fmac_f32_e32 v32, s51, v75
	v_fmac_f32_e32 v32, s52, v76
	v_fmac_f32_e32 v32, s53, v77
	v_fmac_f32_e32 v32, s54, v78
	v_fmac_f32_e32 v32, s55, v79
	s_load_dwordx16 s[40:55], s[24:25], 0x240 glc
	v_min_f32_e32 v33, 0, v32
	v_mul_f32_e64 v34, |v32|, s11
	v_exp_f32_e32 v34, v34
	s_nop 0
	v_add_f32_e32 v34, 1.0, v34
	v_log_f32_e32 v34, v34
	s_nop 0
	v_mul_f32_e32 v34, s12, v34
	v_sub_f32_e32 v33, v33, v34
	v_mul_f32_e32 v118, s13, v33
	v_add_f32_e32 v145, v145, v118
	s_waitcnt lgkmcnt(0)
	v_mov_b32_e32 v32, v80
	v_fmac_f32_e32 v32, s56, v64
	v_fmac_f32_e32 v32, s57, v65
	v_fmac_f32_e32 v32, s58, v66
	v_fmac_f32_e32 v32, s59, v67
	v_fmac_f32_e32 v32, s60, v68
	v_fmac_f32_e32 v32, s61, v69
	v_fmac_f32_e32 v32, s62, v70
	v_fmac_f32_e32 v32, s63, v71
	v_fmac_f32_e32 v32, s64, v72
	v_fmac_f32_e32 v32, s65, v73
	v_fmac_f32_e32 v32, s66, v74
	v_fmac_f32_e32 v32, s67, v75
	v_fmac_f32_e32 v32, s68, v76
	v_fmac_f32_e32 v32, s69, v77
	v_fmac_f32_e32 v32, s70, v78
	v_fmac_f32_e32 v32, s71, v79
	s_load_dwordx16 s[56:71], s[24:25], 0x280 glc
	v_min_f32_e32 v33, 0, v32
	v_mul_f32_e64 v34, |v32|, s11
	v_exp_f32_e32 v34, v34
	s_nop 0
	v_add_f32_e32 v34, 1.0, v34
	v_log_f32_e32 v34, v34
	s_nop 0
	v_mul_f32_e32 v34, s12, v34
	v_sub_f32_e32 v33, v33, v34
	v_mul_f32_e32 v119, s13, v33
	v_add_f32_e32 v145, v145, v119
	s_waitcnt lgkmcnt(0)
	v_mov_b32_e32 v32, v80
	v_fmac_f32_e32 v32, s72, v64
	v_fmac_f32_e32 v32, s73, v65
	v_fmac_f32_e32 v32, s74, v66
	v_fmac_f32_e32 v32, s75, v67
	v_fmac_f32_e32 v32, s76, v68
	v_fmac_f32_e32 v32, s77, v69
	v_fmac_f32_e32 v32, s78, v70
	v_fmac_f32_e32 v32, s79, v71
	v_fmac_f32_e32 v32, s80, v72
	v_fmac_f32_e32 v32, s81, v73
	v_fmac_f32_e32 v32, s82, v74
	v_fmac_f32_e32 v32, s83, v75
	v_fmac_f32_e32 v32, s84, v76
	v_fmac_f32_e32 v32, s85, v77
	v_fmac_f32_e32 v32, s86, v78
	v_fmac_f32_e32 v32, s87, v79
	s_load_dwordx16 s[72:87], s[24:25], 0x2c0 glc
	v_min_f32_e32 v33, 0, v32
	v_mul_f32_e64 v34, |v32|, s11
	v_exp_f32_e32 v34, v34
	s_nop 0
	v_add_f32_e32 v34, 1.0, v34
	v_log_f32_e32 v34, v34
	s_nop 0
	v_mul_f32_e32 v34, s12, v34
	v_sub_f32_e32 v33, v33, v34
	v_mul_f32_e32 v120, s13, v33
	v_add_f32_e32 v145, v145, v120
	s_waitcnt lgkmcnt(0)
	v_mov_b32_e32 v32, v80
	v_fmac_f32_e32 v32, s40, v64
	v_fmac_f32_e32 v32, s41, v65
	v_fmac_f32_e32 v32, s42, v66
	v_fmac_f32_e32 v32, s43, v67
	v_fmac_f32_e32 v32, s44, v68
	v_fmac_f32_e32 v32, s45, v69
	v_fmac_f32_e32 v32, s46, v70
	v_fmac_f32_e32 v32, s47, v71
	v_fmac_f32_e32 v32, s48, v72
	v_fmac_f32_e32 v32, s49, v73
	v_fmac_f32_e32 v32, s50, v74
	v_fmac_f32_e32 v32, s51, v75
	v_fmac_f32_e32 v32, s52, v76
	v_fmac_f32_e32 v32, s53, v77
	v_fmac_f32_e32 v32, s54, v78
	v_fmac_f32_e32 v32, s55, v79
	s_load_dwordx16 s[40:55], s[24:25], 0x300 glc
	v_min_f32_e32 v33, 0, v32
	v_mul_f32_e64 v34, |v32|, s11
	v_exp_f32_e32 v34, v34
	s_nop 0
	v_add_f32_e32 v34, 1.0, v34
	v_log_f32_e32 v34, v34
	s_nop 0
	v_mul_f32_e32 v34, s12, v34
	v_sub_f32_e32 v33, v33, v34
	v_mul_f32_e32 v121, s13, v33
	v_add_f32_e32 v145, v145, v121
	s_waitcnt lgkmcnt(0)
	v_mov_b32_e32 v32, v80
	v_fmac_f32_e32 v32, s56, v64
	v_fmac_f32_e32 v32, s57, v65
	v_fmac_f32_e32 v32, s58, v66
	v_fmac_f32_e32 v32, s59, v67
	v_fmac_f32_e32 v32, s60, v68
	v_fmac_f32_e32 v32, s61, v69
	v_fmac_f32_e32 v32, s62, v70
	v_fmac_f32_e32 v32, s63, v71
	v_fmac_f32_e32 v32, s64, v72
	v_fmac_f32_e32 v32, s65, v73
	v_fmac_f32_e32 v32, s66, v74
	v_fmac_f32_e32 v32, s67, v75
	v_fmac_f32_e32 v32, s68, v76
	v_fmac_f32_e32 v32, s69, v77
	v_fmac_f32_e32 v32, s70, v78
	v_fmac_f32_e32 v32, s71, v79
	s_load_dwordx16 s[56:71], s[24:25], 0x340 glc
	v_min_f32_e32 v33, 0, v32
	v_mul_f32_e64 v34, |v32|, s11
	v_exp_f32_e32 v34, v34
	s_nop 0
	v_add_f32_e32 v34, 1.0, v34
	v_log_f32_e32 v34, v34
	s_nop 0
	v_mul_f32_e32 v34, s12, v34
	v_sub_f32_e32 v33, v33, v34
	v_mul_f32_e32 v122, s13, v33
	v_add_f32_e32 v145, v145, v122
	s_waitcnt lgkmcnt(0)
	v_mov_b32_e32 v32, v80
	v_fmac_f32_e32 v32, s72, v64
	v_fmac_f32_e32 v32, s73, v65
	v_fmac_f32_e32 v32, s74, v66
	v_fmac_f32_e32 v32, s75, v67
	v_fmac_f32_e32 v32, s76, v68
	v_fmac_f32_e32 v32, s77, v69
	v_fmac_f32_e32 v32, s78, v70
	v_fmac_f32_e32 v32, s79, v71
	v_fmac_f32_e32 v32, s80, v72
	v_fmac_f32_e32 v32, s81, v73
	v_fmac_f32_e32 v32, s82, v74
	v_fmac_f32_e32 v32, s83, v75
	v_fmac_f32_e32 v32, s84, v76
	v_fmac_f32_e32 v32, s85, v77
	v_fmac_f32_e32 v32, s86, v78
	v_fmac_f32_e32 v32, s87, v79
	s_load_dwordx16 s[72:87], s[24:25], 0x380 glc
	v_min_f32_e32 v33, 0, v32
	v_mul_f32_e64 v34, |v32|, s11
	v_exp_f32_e32 v34, v34
	s_nop 0
	v_add_f32_e32 v34, 1.0, v34
	v_log_f32_e32 v34, v34
	s_nop 0
	v_mul_f32_e32 v34, s12, v34
	v_sub_f32_e32 v33, v33, v34
	v_mul_f32_e32 v123, s13, v33
	v_add_f32_e32 v145, v145, v123
	s_waitcnt lgkmcnt(0)
	v_mov_b32_e32 v32, v80
	v_fmac_f32_e32 v32, s40, v64
	v_fmac_f32_e32 v32, s41, v65
	v_fmac_f32_e32 v32, s42, v66
	v_fmac_f32_e32 v32, s43, v67
	v_fmac_f32_e32 v32, s44, v68
	v_fmac_f32_e32 v32, s45, v69
	v_fmac_f32_e32 v32, s46, v70
	v_fmac_f32_e32 v32, s47, v71
	v_fmac_f32_e32 v32, s48, v72
	v_fmac_f32_e32 v32, s49, v73
	v_fmac_f32_e32 v32, s50, v74
	v_fmac_f32_e32 v32, s51, v75
	v_fmac_f32_e32 v32, s52, v76
	v_fmac_f32_e32 v32, s53, v77
	v_fmac_f32_e32 v32, s54, v78
	v_fmac_f32_e32 v32, s55, v79
	s_load_dwordx16 s[40:55], s[24:25], 0x3c0 glc
	v_min_f32_e32 v33, 0, v32
	v_mul_f32_e64 v34, |v32|, s11
	v_exp_f32_e32 v34, v34
	s_nop 0
	v_add_f32_e32 v34, 1.0, v34
	v_log_f32_e32 v34, v34
	s_nop 0
	v_mul_f32_e32 v34, s12, v34
	v_sub_f32_e32 v33, v33, v34
	v_mul_f32_e32 v124, s13, v33
	v_add_f32_e32 v145, v145, v124
	s_waitcnt lgkmcnt(0)
	v_mov_b32_e32 v32, v80
	v_fmac_f32_e32 v32, s56, v64
	v_fmac_f32_e32 v32, s57, v65
	v_fmac_f32_e32 v32, s58, v66
	v_fmac_f32_e32 v32, s59, v67
	v_fmac_f32_e32 v32, s60, v68
	v_fmac_f32_e32 v32, s61, v69
	v_fmac_f32_e32 v32, s62, v70
	v_fmac_f32_e32 v32, s63, v71
	v_fmac_f32_e32 v32, s64, v72
	v_fmac_f32_e32 v32, s65, v73
	v_fmac_f32_e32 v32, s66, v74
	v_fmac_f32_e32 v32, s67, v75
	v_fmac_f32_e32 v32, s68, v76
	v_fmac_f32_e32 v32, s69, v77
	v_fmac_f32_e32 v32, s70, v78
	v_fmac_f32_e32 v32, s71, v79
	v_min_f32_e32 v33, 0, v32
	v_mul_f32_e64 v34, |v32|, s11
	v_exp_f32_e32 v34, v34
	s_nop 0
	v_add_f32_e32 v34, 1.0, v34
	v_log_f32_e32 v34, v34
	s_nop 0
	v_mul_f32_e32 v34, s12, v34
	v_sub_f32_e32 v33, v33, v34
	v_mul_f32_e32 v125, s13, v33
	v_add_f32_e32 v145, v145, v125
	s_waitcnt lgkmcnt(0)
	v_mov_b32_e32 v32, v80
	v_fmac_f32_e32 v32, s72, v64
	v_fmac_f32_e32 v32, s73, v65
	v_fmac_f32_e32 v32, s74, v66
	v_fmac_f32_e32 v32, s75, v67
	v_fmac_f32_e32 v32, s76, v68
	v_fmac_f32_e32 v32, s77, v69
	v_fmac_f32_e32 v32, s78, v70
	v_fmac_f32_e32 v32, s79, v71
	v_fmac_f32_e32 v32, s80, v72
	v_fmac_f32_e32 v32, s81, v73
	v_fmac_f32_e32 v32, s82, v74
	v_fmac_f32_e32 v32, s83, v75
	v_fmac_f32_e32 v32, s84, v76
	v_fmac_f32_e32 v32, s85, v77
	v_fmac_f32_e32 v32, s86, v78
	v_fmac_f32_e32 v32, s87, v79
	v_min_f32_e32 v33, 0, v32
	v_mul_f32_e64 v34, |v32|, s11
	v_exp_f32_e32 v34, v34
	s_nop 0
	v_add_f32_e32 v34, 1.0, v34
	v_log_f32_e32 v34, v34
	s_nop 0
	v_mul_f32_e32 v34, s12, v34
	v_sub_f32_e32 v33, v33, v34
	v_mul_f32_e32 v126, s13, v33
	v_add_f32_e32 v145, v145, v126
	s_waitcnt lgkmcnt(0)
	v_mov_b32_e32 v32, v80
	v_fmac_f32_e32 v32, s40, v64
	v_fmac_f32_e32 v32, s41, v65
	v_fmac_f32_e32 v32, s42, v66
	v_fmac_f32_e32 v32, s43, v67
	v_fmac_f32_e32 v32, s44, v68
	v_fmac_f32_e32 v32, s45, v69
	v_fmac_f32_e32 v32, s46, v70
	v_fmac_f32_e32 v32, s47, v71
	v_fmac_f32_e32 v32, s48, v72
	v_fmac_f32_e32 v32, s49, v73
	v_fmac_f32_e32 v32, s50, v74
	v_fmac_f32_e32 v32, s51, v75
	v_fmac_f32_e32 v32, s52, v76
	v_fmac_f32_e32 v32, s53, v77
	v_fmac_f32_e32 v32, s54, v78
	v_fmac_f32_e32 v32, s55, v79
	v_min_f32_e32 v33, 0, v32
	v_mul_f32_e64 v34, |v32|, s11
	v_exp_f32_e32 v34, v34
	s_nop 0
	v_add_f32_e32 v34, 1.0, v34
	v_log_f32_e32 v34, v34
	s_nop 0
	v_mul_f32_e32 v34, s12, v34
	v_sub_f32_e32 v33, v33, v34
	v_mul_f32_e32 v127, s13, v33
	v_add_f32_e32 v145, v145, v127
.Lpre_g_exch:
	s_barrier
	ds_write_b32 v144, v145
	s_waitcnt lgkmcnt(0)
	s_barrier
	ds_read_b32 v132, v142
	ds_read_b32 v133, v142 offset:256
	ds_read_b32 v134, v142 offset:512
	ds_read_b32 v135, v142 offset:768
	s_waitcnt lgkmcnt(0)
	v_add_f32_e32 v136, v132, v133
	v_add_f32_e32 v136, v136, v134
	v_add_f32_e32 v136, v136, v135
	v_mov_b32_e32 v145, 0
	s_cmp_eq_u32 s17, 0
	s_cbranch_scc0 .Lpre_g_tpn
	s_mul_i32 s21, s19, 0xc00
	s_lshl_b32 s4, s18, 8
	s_add_u32 s21, s21, s4
	s_add_u32 s21, s21, 0x800
	s_add_u32 s22, s21, 0x28d00000
	s_add_u32 s36, s94, s22
	s_addc_u32 s37, s95, 0
	v_mul_f32_e32 v32, s10, v136
	v_exp_f32_e32 v32, v32
	s_nop 0
	global_store_dword v142, v32, s[36:37]
	s_branch .Lpre_g_p2
.Lpre_g_tpn:
	v_mov_b32_e32 v145, v132
	s_cmp_lt_u32 s17, 2
	s_cbranch_scc1 .Lpre_g_p2
	v_add_f32_e32 v145, v145, v133
	s_cmp_lt_u32 s17, 3
	s_cbranch_scc1 .Lpre_g_p2
	v_add_f32_e32 v145, v145, v134
.Lpre_g_p2:
	s_cmp_eq_u32 s23, 0
	s_cbranch_scc1 .Lpre_g_next
	s_waitcnt vmcnt(0)
	v_lshlrev_b32_e32 v96, 16, v96
	v_lshlrev_b32_e32 v97, 16, v97
	v_lshlrev_b32_e32 v98, 16, v98
	v_lshlrev_b32_e32 v99, 16, v99
	v_lshlrev_b32_e32 v100, 16, v100
	v_lshlrev_b32_e32 v101, 16, v101
	v_lshlrev_b32_e32 v102, 16, v102
	v_lshlrev_b32_e32 v103, 16, v103
	v_lshlrev_b32_e32 v104, 16, v104
	v_lshlrev_b32_e32 v105, 16, v105
	v_lshlrev_b32_e32 v106, 16, v106
	v_lshlrev_b32_e32 v107, 16, v107
	v_lshlrev_b32_e32 v108, 16, v108
	v_lshlrev_b32_e32 v109, 16, v109
	v_lshlrev_b32_e32 v110, 16, v110
	v_lshlrev_b32_e32 v111, 16, v111
	v_add_f32_e32 v32, v145, v112
	v_add_f32_e32 v33, v32, v113
	v_add_f32_e32 v34, v33, v114
	v_add_f32_e32 v35, v34, v115
	v_mov_b32_e32 v145, v35
	v_mul_f32_e32 v32, s10, v32
	v_mul_f32_e32 v33, s10, v33
	v_mul_f32_e32 v34, s10, v34
	v_mul_f32_e32 v35, s10, v35
	v_exp_f32_e32 v36, v32
	v_exp_f32_e32 v37, v33
	v_exp_f32_e32 v38, v34
	v_exp_f32_e32 v39, v35
	v_exp_f32_e64 v40, -v32
	v_exp_f32_e64 v41, -v33
	v_exp_f32_e64 v42, -v34
	v_exp_f32_e64 v43, -v35
	v_lshlrev_b32_e32 v44, 16, v0
	v_lshlrev_b32_e32 v45, 16, v1
	v_lshlrev_b32_e32 v46, 16, v2
	v_lshlrev_b32_e32 v47, 16, v3
	v_mul_f32_e32 v36, v44, v36
	v_mul_f32_e32 v37, v45, v37
	v_mul_f32_e32 v38, v46, v38
	v_mul_f32_e32 v39, v47, v39
	v_mul_f32_e32 v40, v96, v40
	v_mul_f32_e32 v41, v97, v41
	v_mul_f32_e32 v42, v98, v42
	v_mul_f32_e32 v43, v99, v43
	v_cvt_pk_bf16_f32 v44, v36, v40
	v_cvt_pk_bf16_f32 v45, v37, v41
	v_cvt_pk_bf16_f32 v46, v38, v42
	v_cvt_pk_bf16_f32 v47, v39, v43
	s_nop 0
	global_store_short v143, v44, s[28:29]
	global_store_short_d16_hi v143, v44, s[30:31]
	global_store_short v143, v45, s[28:29] offset:512
	global_store_short_d16_hi v143, v45, s[30:31] offset:512
	global_store_short v143, v46, s[28:29] offset:1024
	global_store_short_d16_hi v143, v46, s[30:31] offset:1024
	global_store_short v143, v47, s[28:29] offset:1536
	global_store_short_d16_hi v143, v47, s[30:31] offset:1536
	v_add_f32_e32 v32, v145, v116
	v_add_f32_e32 v33, v32, v117
	v_add_f32_e32 v34, v33, v118
	v_add_f32_e32 v35, v34, v119
	v_mov_b32_e32 v145, v35
	v_mul_f32_e32 v32, s10, v32
	v_mul_f32_e32 v33, s10, v33
	v_mul_f32_e32 v34, s10, v34
	v_mul_f32_e32 v35, s10, v35
	v_exp_f32_e32 v36, v32
	v_exp_f32_e32 v37, v33
	v_exp_f32_e32 v38, v34
	v_exp_f32_e32 v39, v35
	v_exp_f32_e64 v40, -v32
	v_exp_f32_e64 v41, -v33
	v_exp_f32_e64 v42, -v34
	v_exp_f32_e64 v43, -v35
	v_lshlrev_b32_e32 v44, 16, v4
	v_lshlrev_b32_e32 v45, 16, v5
	v_lshlrev_b32_e32 v46, 16, v6
	v_lshlrev_b32_e32 v47, 16, v7
	v_mul_f32_e32 v36, v44, v36
	v_mul_f32_e32 v37, v45, v37
	v_mul_f32_e32 v38, v46, v38
	v_mul_f32_e32 v39, v47, v39
	v_mul_f32_e32 v40, v100, v40
	v_mul_f32_e32 v41, v101, v41
	v_mul_f32_e32 v42, v102, v42
	v_mul_f32_e32 v43, v103, v43
	v_cvt_pk_bf16_f32 v44, v36, v40
	v_cvt_pk_bf16_f32 v45, v37, v41
	v_cvt_pk_bf16_f32 v46, v38, v42
	v_cvt_pk_bf16_f32 v47, v39, v43
	s_nop 0
	global_store_short v143, v44, s[28:29] offset:2048
	global_store_short_d16_hi v143, v44, s[30:31] offset:2048
	global_store_short v143, v45, s[28:29] offset:2560
	global_store_short_d16_hi v143, v45, s[30:31] offset:2560
	global_store_short v143, v46, s[28:29] offset:3072
	global_store_short_d16_hi v143, v46, s[30:31] offset:3072
	global_store_short v143, v47, s[28:29] offset:3584
	global_store_short_d16_hi v143, v47, s[30:31] offset:3584
	s_add_u32 s28, s28, 0x1000
	s_addc_u32 s29, s29, 0
	s_add_u32 s30, s30, 0x1000
	s_addc_u32 s31, s31, 0
	v_add_f32_e32 v32, v145, v120
	v_add_f32_e32 v33, v32, v121
	v_add_f32_e32 v34, v33, v122
	v_add_f32_e32 v35, v34, v123
	v_mov_b32_e32 v145, v35
	v_mul_f32_e32 v32, s10, v32
	v_mul_f32_e32 v33, s10, v33
	v_mul_f32_e32 v34, s10, v34
	v_mul_f32_e32 v35, s10, v35
	v_exp_f32_e32 v36, v32
	v_exp_f32_e32 v37, v33
	v_exp_f32_e32 v38, v34
	v_exp_f32_e32 v39, v35
	v_exp_f32_e64 v40, -v32
	v_exp_f32_e64 v41, -v33
	v_exp_f32_e64 v42, -v34
	v_exp_f32_e64 v43, -v35
	v_lshlrev_b32_e32 v44, 16, v8
	v_lshlrev_b32_e32 v45, 16, v9
	v_lshlrev_b32_e32 v46, 16, v10
	v_lshlrev_b32_e32 v47, 16, v11
	v_mul_f32_e32 v36, v44, v36
	v_mul_f32_e32 v37, v45, v37
	v_mul_f32_e32 v38, v46, v38
	v_mul_f32_e32 v39, v47, v39
	v_mul_f32_e32 v40, v104, v40
	v_mul_f32_e32 v41, v105, v41
	v_mul_f32_e32 v42, v106, v42
	v_mul_f32_e32 v43, v107, v43
	v_cvt_pk_bf16_f32 v44, v36, v40
	v_cvt_pk_bf16_f32 v45, v37, v41
	v_cvt_pk_bf16_f32 v46, v38, v42
	v_cvt_pk_bf16_f32 v47, v39, v43
	s_nop 0
	global_store_short v143, v44, s[28:29]
	global_store_short_d16_hi v143, v44, s[30:31]
	global_store_short v143, v45, s[28:29] offset:512
	global_store_short_d16_hi v143, v45, s[30:31] offset:512
	global_store_short v143, v46, s[28:29] offset:1024
	global_store_short_d16_hi v143, v46, s[30:31] offset:1024
	global_store_short v143, v47, s[28:29] offset:1536
	global_store_short_d16_hi v143, v47, s[30:31] offset:1536
	v_add_f32_e32 v32, v145, v124
	v_add_f32_e32 v33, v32, v125
	v_add_f32_e32 v34, v33, v126
	v_add_f32_e32 v35, v34, v127
	v_mov_b32_e32 v145, v35
	v_mul_f32_e32 v32, s10, v32
	v_mul_f32_e32 v33, s10, v33
	v_mul_f32_e32 v34, s10, v34
	v_mul_f32_e32 v35, s10, v35
	v_exp_f32_e32 v36, v32
	v_exp_f32_e32 v37, v33
	v_exp_f32_e32 v38, v34
	v_exp_f32_e32 v39, v35
	v_exp_f32_e64 v40, -v32
	v_exp_f32_e64 v41, -v33
	v_exp_f32_e64 v42, -v34
	v_exp_f32_e64 v43, -v35
	v_lshlrev_b32_e32 v44, 16, v12
	v_lshlrev_b32_e32 v45, 16, v13
	v_lshlrev_b32_e32 v46, 16, v14
	v_lshlrev_b32_e32 v47, 16, v15
	v_mul_f32_e32 v36, v44, v36
	v_mul_f32_e32 v37, v45, v37
	v_mul_f32_e32 v38, v46, v38
	v_mul_f32_e32 v39, v47, v39
	v_mul_f32_e32 v40, v108, v40
	v_mul_f32_e32 v41, v109, v41
	v_mul_f32_e32 v42, v110, v42
	v_mul_f32_e32 v43, v111, v43
	v_cvt_pk_bf16_f32 v44, v36, v40
	v_cvt_pk_bf16_f32 v45, v37, v41
	v_cvt_pk_bf16_f32 v46, v38, v42
	v_cvt_pk_bf16_f32 v47, v39, v43
	s_nop 0
	global_store_short v143, v44, s[28:29] offset:2048
	global_store_short_d16_hi v143, v44, s[30:31] offset:2048
	global_store_short v143, v45, s[28:29] offset:2560
	global_store_short_d16_hi v143, v45, s[30:31] offset:2560
	global_store_short v143, v46, s[28:29] offset:3072
	global_store_short_d16_hi v143, v46, s[30:31] offset:3072
	global_store_short v143, v47, s[28:29] offset:3584
	global_store_short_d16_hi v143, v47, s[30:31] offset:3584
